# GEMM K-loops: per-segment s_setprio flips removed, one static s_setprio 1 for waves 0-3 (other half) before each loop; on top of v42
# speedup vs baseline: 1.0066x; 1.0014x over previous
;     DI const char* aptr(const Unit& u) const { return A + (size_t)u.pm * ta + (size_t)kofs(u.seg) * 2; }
;     DI const char* bptr(const Unit& u) const { return B + (size_t)u.pn * tb + (size_t)kofs(u.seg) * 2; }
; #define PG8_STAGE(bufoff, gbase, voff) do { _Pragma("unroll") for (int _i = 0; _i < 2; ++_i) \
;         __builtin_amdgcn_global_load_lds((const unsigned*)((const char*)(gbase) + (voff)[_i]), (LAS unsigned*)(lds + (bufoff) + ldsw + _i * 8192), 16, 0, 0); } while (0)
; #define PG8_WAIT_V(n) asm volatile("s_waitcnt vmcnt(" #n ")" ::: "memory")
; #define PG8_BAR __builtin_amdgcn_s_barrier()
; template <class Epi, class Sched>
; DI void gemm_phase(LAS unsigned char* lds, const int wv, const int lda, const int ldb, const Sched& S, const Epi& E) {
;     ...
;     const int tid = tid_, wid = __builtin_amdgcn_readfirstlane(tid >> 6), lane = tid & 63, wr = wid >> 2, wc = wid & 3, fr = lane & 15, fq = lane >> 4;
;     unsigned voffA[2], voffB[2];
; #pragma unroll
;     for (int i = 0; i < 2; ++i) { int R, C; stage_rc(tid * 16 + i * 8192, R, C); const int Rb = Epi::PERM ? ((R & ~31) + perm32(R & 31)) : R;
;         voffA[i] = (unsigned)(R * lda + C) * 2u; voffB[i] = (unsigned)(Rb * ldb + C) * 2u; }
;     const size_t kstep = (size_t)(BK * 2);
;     const size_t hstepA = (size_t)HALF * lda * 2, hstepB = (size_t)HALF * ldb * 2;
;     const unsigned ldsw = (unsigned)wid * 1024u;
;     const int aoff = lds_byte(wr * 64 + fr, fq * 8), boff = lds_byte(wc * 32 + fr, fq * 8);
;     ...
;     const char* cA = S.aptr(cur); const char* cB = S.bptr(cur); int nt = S.ntiles(cur);
;     PG8_STAGE(PG8_SB(0, 0), cB, voffB); PG8_STAGE(PG8_SB(0, 1), cB + hstepB, voffB); PG8_STAGE(PG8_SA(0, 0), cA, voffA); PG8_STAGE(PG8_SA(0, 1), cA + hstepA, voffA);
;     if (wr == 1) PG8_BAR;
;     PG8_WAIT_V(2); PG8_BAR;
;     PG8_STAGE(PG8_SB(1, 0), cB + kstep, voffB); PG8_STAGE(PG8_SA(1, 0), cA + kstep, voffA); PG8_STAGE(PG8_SB(1, 1), cB + hstepB + kstep, voffB);
;     PG8_WAIT_V(6); PG8_BAR;
.LBB0_372:
	s_lshl_b32 s5, s43, 13
	s_and_b32 s5, s5, 0xe000
	s_sub_i32 s51, 0, s5
	s_add_i32 s51, s51, 0x20000
	s_add_u32 s6, s10, 0x23c28000
	s_mul_i32 s16, s71, 0x1800
	s_mov_b32 s17, s21
	s_addc_u32 s7, s11, 0
	s_lshl_b64 s[16:17], s[16:17], 2
	s_waitcnt lgkmcnt(0)
	s_add_u32 s12, s12, s16
	s_addc_u32 s13, s13, s17
	s_add_u32 s10, s10, 0x561b8000
	s_addc_u32 s11, s11, 0
	s_lshl_b32 s15, s15, 5
	s_and_b32 s18, s15, 0x60
	s_add_i32 m0, s31, 0x18000
	v_lshl_add_u64 v[6:7], v[6:7], 0, s[28:29]
	s_lshl_b32 s5, s14, 13
	s_lshl_b32 s15, s18, 7
	s_waitcnt vmcnt(2)
	s_barrier
	global_load_lds_dwordx4 v[6:7], off
	v_lshl_add_u64 v[4:5], v[4:5], 0, s[28:29]
	s_add_i32 m0, s31, 0x1a000
	s_add_i32 s52, s31, 0x8000
	s_add_i32 s53, s31, 0xa000
	global_load_lds_dwordx4 v[4:5], off
	v_lshl_add_u64 v[0:1], v[0:1], 0, s[28:29]
	s_mov_b32 m0, s52
	s_add_u32 s16, s36, 0x80080
	global_load_lds_dwordx4 v[0:1], off
	v_lshl_add_u64 v[0:1], v[2:3], 0, s[28:29]
	s_mov_b32 m0, s53
	s_addc_u32 s17, s37, 0
	global_load_lds_dwordx4 v[0:1], off
	s_add_i32 m0, s31, 0x1c000
	v_lshl_add_u64 v[0:1], s[16:17], 0, v[138:139]
	global_load_lds_dwordx4 v[0:1], off
	v_lshl_add_u64 v[0:1], s[16:17], 0, v[142:143]
	s_add_i32 m0, s31, 0x1e000
	s_cmpk_lt_u32 s1, 0x100
	global_load_lds_dwordx4 v[0:1], off
	v_lshrrev_b32_e32 v1, 1, v8
	v_and_b32_e32 v2, 24, v1
	v_and_b32_e32 v0, 15, v8
	v_lshlrev_b32_e32 v3, 1, v2
	v_lshl_or_b32 v145, s14, 6, v0
	v_lshl_or_b32 v0, v0, 6, v3
	v_lshlrev_b32_e32 v3, 2, v8
	v_and_b32_e32 v3, 32, v3
	v_bitop3_b32 v170, v0, s15, v3 bitop3:0xde
	s_cselect_b64 s[14:15], -1, 0
	s_lshl_b32 s54, s0, 3
	s_abs_i32 s55, s54
	v_bitop3_b32 v4, v0, s5, v3 bitop3:0xde
	v_cvt_f32_u32_e32 v0, s55
	v_and_b32_e32 v144, 8, v1
	v_and_b32_e32 v1, 1, v9
	s_bfe_i32 s58, s0, 0x1001c
	v_rcp_iflag_f32_e32 v0, v0
	s_sub_i32 s0, 0, s55
	s_waitcnt vmcnt(6)
	s_ashr_i32 s56, s44, 31
	v_mul_f32_e32 v0, 0x4f7ffffe, v0
	v_cvt_u32_f32_e32 v0, v0
	s_ashr_i32 s57, s43, 31
	v_or_b32_e32 v171, s18, v2
	s_mov_b32 s59, 0
	v_readfirstlane_b32 s1, v0
	v_lshlrev_b32_e32 v0, 15, v9
	v_and_b32_e32 v0, 0xffff0000, v0
	v_lshl_add_u32 v0, v10, 12, v0
	v_lshl_or_b32 v0, v1, 6, v0
	v_lshl_add_u32 v146, v11, 1, v0
	v_lshlrev_b32_e32 v0, 15, v12
	v_and_b32_e32 v0, 0xffff0000, v0
	s_mul_i32 s0, s0, s1
	v_lshl_add_u32 v0, v13, 12, v0
	v_and_b32_e32 v1, 1, v12
	s_mul_hi_u32 s0, s1, s0
	v_lshl_or_b32 v0, v1, 6, v0
	s_add_i32 s67, s1, s0
	v_mov_b32_e32 v147, v185
	v_lshl_add_u32 v148, v14, 1, v0
	v_mov_b32_e32 v149, v185
	v_add_u32_e32 v172, 0, v4
	s_barrier
	s_cmp_ge_u32 s90, 4
	s_cbranch_scc1 .Lprio_375_done
	s_setprio 1

;     DI bool next(int i, Unit& u) const { const long L = (long)i * G + c; if (L >= T.nwg) return false; T.map((int)L, u.pm, u.pn); u.seg = 0; return true; }
;     DI bool next(int i, Unit& u) const { const int ti = i / 3; const long L = (long)ti * G + c; if (L >= T.nwg) return false; T.map((int)L, u.pm, u.pn); u.seg = i - 3 * ti; return true; }
;     DI const char* aptr(const Unit& u) const { return A + (size_t)u.pm * ta + (size_t)kofs(u.seg) * 2; }
;     DI const char* bptr(const Unit& u) const { return B + (size_t)u.pn * tb + (size_t)kofs(u.seg) * 2; }
; #define PG8_WAIT_V(n) asm volatile("s_waitcnt vmcnt(" #n ")" ::: "memory")
; #define PG8_BAR __builtin_amdgcn_s_barrier()
; template <class Epi, class Sched>
; DI void gemm_phase(LAS unsigned char* lds, const int wv, const int lda, const int ldb, const Sched& S, const Epi& E) {
;     ...
;     for (int i = 0; i < 2; ++i) { int R, C; stage_rc(tid * 16 + i * 8192, R, C); const int Rb = Epi::PERM ? ((R & ~31) + perm32(R & 31)) : R;
;         voffA[i] = (unsigned)(R * lda + C) * 2u; voffB[i] = (unsigned)(Rb * ldb + C) * 2u; }
;     const size_t kstep = (size_t)(BK * 2);
;     const size_t hstepA = (size_t)HALF * lda * 2, hstepB = (size_t)HALF * ldb * 2;
;     const unsigned ldsw = (unsigned)wid * 1024u;
;     const int aoff = lds_byte(wr * 64 + fr, fq * 8), boff = lds_byte(wc * 32 + fr, fq * 8);
;     ...
;     Unit cur, nxt; int ui = 0;
;     if (!S.next(0, cur)) return;
;     f32x4 acc[2][2][4][2];
; #pragma unroll
;     for (int a = 0; a < 2; ++a)
; #pragma unroll
;         for (int b = 0; b < 2; ++b)
; #pragma unroll
;             for (int m = 0; m < 4; ++m)
; #pragma unroll
;                 for (int n = 0; n < 2; ++n) acc[a][b][m][n] = (f32x4){0.f, 0.f, 0.f, 0.f};
;     bf16x8 At[4][2], B0[2][2], B1[2][2];
;     const char* cA = S.aptr(cur); const char* cB = S.bptr(cur); int nt = S.ntiles(cur);
;     PG8_STAGE(PG8_SB(0, 0), cB, voffB); PG8_STAGE(PG8_SB(0, 1), cB + hstepB, voffB); PG8_STAGE(PG8_SA(0, 0), cA, voffA); PG8_STAGE(PG8_SA(0, 1), cA + hstepA, voffA);
;     if (wr == 1) PG8_BAR;
;     PG8_WAIT_V(2); PG8_BAR;
;     PG8_STAGE(PG8_SB(1, 0), cB + kstep, voffB); PG8_STAGE(PG8_SA(1, 0), cA + kstep, voffA); PG8_STAGE(PG8_SB(1, 1), cB + hstepB + kstep, voffB);
;     PG8_WAIT_V(6); PG8_BAR;
.LBB0_1089:
	s_sext_i32_i8 s48, s10
	s_add_u32 s10, s6, 0x3a428000
	s_mul_i32 s20, s71, 0x300
	s_addc_u32 s11, s7, 0
	s_lshl_b64 s[6:7], s[20:21], 2
	s_add_u32 s12, s4, s6
	v_lshrrev_b32_e32 v18, 1, v14
	s_addc_u32 s13, s5, s7
	v_and_b32_e32 v18, 24, v18
	s_lshl_b32 s0, s0, 5
	v_and_b32_e32 v17, 15, v14
	v_lshlrev_b32_e32 v19, 1, v18
	v_lshlrev_b32_e32 v14, 2, v14
	s_and_b32 s4, s0, 0x60
	s_add_i32 m0, s38, 0x18000
	v_lshl_add_u64 v[6:7], v[6:7], 0, s[28:29]
	v_lshl_or_b32 v186, s1, 6, v17
	v_lshl_or_b32 v17, v17, 6, v19
	s_lshl_b32 s1, s1, 13
	v_and_b32_e32 v14, 32, v14
	s_lshl_b32 s0, s4, 7
	s_waitcnt vmcnt(2)
	s_barrier
	global_load_lds_dwordx4 v[6:7], off
	v_lshl_add_u64 v[4:5], v[4:5], 0, s[28:29]
	s_add_i32 m0, s38, 0x1a000
	s_add_i32 s20, s38, 0x8000
	s_add_i32 s42, s38, 0xa000
	v_bitop3_b32 v204, v17, s0, v14 bitop3:0xde
	global_load_lds_dwordx4 v[4:5], off
	v_lshl_add_u64 v[0:1], v[0:1], 0, s[28:29]
	s_mov_b32 m0, s20
	s_add_u32 s0, s24, 0x30080
	v_bitop3_b32 v19, v17, s1, v14 bitop3:0xde
	global_load_lds_dwordx4 v[0:1], off
	v_lshl_add_u64 v[0:1], v[2:3], 0, s[28:29]
	s_mov_b32 m0, s42
	s_addc_u32 s1, s25, 0
	global_load_lds_dwordx4 v[0:1], off
	s_add_i32 m0, s38, 0x1c000
	v_lshl_add_u64 v[0:1], s[0:1], 0, v[184:185]
	global_load_lds_dwordx4 v[0:1], off
	v_lshl_add_u64 v[0:1], s[0:1], 0, v[168:169]
	s_add_i32 m0, s38, 0x1e000
	s_movk_i32 s5, 0x300
	global_load_lds_dwordx4 v[0:1], off
	v_or_b32_e32 v205, s4, v18
	v_lshrrev_b32_e32 v1, 1, v13
	v_mul_lo_u32 v0, v12, s5
	s_movk_i32 s4, 0x3000
	v_mad_u64_u32 v[0:1], s[0:1], v1, s4, v[0:1]
	v_or_b32_e32 v0, v0, v15
	v_add_lshl_u32 v0, v0, v16, 1
	v_mov_b32_e32 v1, v185
	s_mov_b64 s[6:7], 0x30080
	v_lshl_add_u64 v[174:175], v[0:1], 0, s[6:7]
	v_lshrrev_b32_e32 v1, 1, v8
	v_mul_lo_u32 v0, v9, s5
	v_mad_u64_u32 v[0:1], s[0:1], v1, s4, v[0:1]
	s_waitcnt vmcnt(6)
	v_or_b32_e32 v0, v0, v10
	s_cmpk_lt_u32 s14, 0x100
	v_add_lshl_u32 v0, v0, v11, 1
	v_mov_b32_e32 v1, v185
	s_cselect_b64 s[14:15], -1, 0
	s_ashr_i32 s43, s33, 31
	v_lshl_add_u64 v[176:177], v[0:1], 0, s[6:7]
	s_mov_b32 s44, 0
	v_add_u32_e32 v206, 0, v19
	s_barrier
	s_cmp_ge_u32 s90, 4
	s_cbranch_scc1 .Lprio_1092_done
	s_setprio 1

;     DI bool next(int i, Unit& u) const { const long L = (long)i * G + c; if (L >= T.nwg) return false; T.map((int)L, u.pm, u.pn); u.seg = 0; return true; }
;     DI bool next(int i, Unit& u) const { const int ti = i / 3; const long L = (long)ti * G + c; if (L >= T.nwg) return false; T.map((int)L, u.pm, u.pn); u.seg = i - 3 * ti; return true; }
;     DI const char* aptr(const Unit& u) const { return A + (size_t)u.pm * ta + (size_t)kofs(u.seg) * 2; }
;     DI const char* bptr(const Unit& u) const { return B + (size_t)u.pn * tb + (size_t)kofs(u.seg) * 2; }
; #define PG8_STAGE(bufoff, gbase, voff) do { _Pragma("unroll") for (int _i = 0; _i < 2; ++_i) \
;         __builtin_amdgcn_global_load_lds((const unsigned*)((const char*)(gbase) + (voff)[_i]), (LAS unsigned*)(lds + (bufoff) + ldsw + _i * 8192), 16, 0, 0); } while (0)
; #define PG8_WAIT_V(n) asm volatile("s_waitcnt vmcnt(" #n ")" ::: "memory")
; #define PG8_BAR __builtin_amdgcn_s_barrier()
; template <class Epi, class Sched>
; DI void gemm_phase(LAS unsigned char* lds, const int wv, const int lda, const int ldb, const Sched& S, const Epi& E) {
;     ...
;     Unit cur, nxt; int ui = 0;
;     if (!S.next(0, cur)) return;
;     f32x4 acc[2][2][4][2];
; #pragma unroll
;     for (int a = 0; a < 2; ++a)
; #pragma unroll
;         for (int b = 0; b < 2; ++b)
; #pragma unroll
;             for (int m = 0; m < 4; ++m)
; #pragma unroll
;                 for (int n = 0; n < 2; ++n) acc[a][b][m][n] = (f32x4){0.f, 0.f, 0.f, 0.f};
;     bf16x8 At[4][2], B0[2][2], B1[2][2];
;     const char* cA = S.aptr(cur); const char* cB = S.bptr(cur); int nt = S.ntiles(cur);
;     PG8_STAGE(PG8_SB(0, 0), cB, voffB); PG8_STAGE(PG8_SB(0, 1), cB + hstepB, voffB); PG8_STAGE(PG8_SA(0, 0), cA, voffA); PG8_STAGE(PG8_SA(0, 1), cA + hstepA, voffA);
;     if (wr == 1) PG8_BAR;
;     PG8_WAIT_V(2); PG8_BAR;
;     PG8_STAGE(PG8_SB(1, 0), cB + kstep, voffB); PG8_STAGE(PG8_SA(1, 0), cA + kstep, voffA); PG8_STAGE(PG8_SB(1, 1), cB + hstepB + kstep, voffB);
;     PG8_WAIT_V(6); PG8_BAR;
.LBB0_1171:
	s_add_u32 s8, s4, 0x23c28000
	v_lshrrev_b32_e32 v16, 1, v8
	s_addc_u32 s9, s5, 0
	v_and_b32_e32 v16, 24, v16
	s_add_u32 s10, s4, 0x1fc28000
	v_and_b32_e32 v15, 15, v8
	v_lshlrev_b32_e32 v17, 1, v16
	v_lshlrev_b32_e32 v8, 2, v8
	s_addc_u32 s11, s5, 0
	v_lshl_or_b32 v186, s0, 6, v15
	v_lshl_or_b32 v15, v15, 6, v17
	s_lshl_b32 s0, s0, 13
	v_and_b32_e32 v8, 32, v8
	v_bitop3_b32 v17, v15, s0, v8 bitop3:0xde
	s_lshl_b32 s0, s1, 5
	s_and_b32 s4, s0, 0x60
	s_add_i32 m0, s45, 0x18000
	v_lshl_add_u64 v[6:7], v[6:7], 0, s[28:29]
	s_lshl_b32 s0, s4, 7
	s_waitcnt vmcnt(2)
	s_barrier
	global_load_lds_dwordx4 v[6:7], off
	v_lshl_add_u64 v[4:5], v[4:5], 0, s[28:29]
	s_add_i32 m0, s45, 0x1a000
	s_add_i32 s49, s45, 0x8000
	s_add_i32 s50, s45, 0xa000
	v_bitop3_b32 v233, v15, s0, v8 bitop3:0xde
	global_load_lds_dwordx4 v[4:5], off
	v_lshl_add_u64 v[0:1], v[0:1], 0, s[28:29]
	s_mov_b32 m0, s49
	s_add_u32 s0, s34, 0x80080
	global_load_lds_dwordx4 v[0:1], off
	v_lshl_add_u64 v[0:1], v[2:3], 0, s[28:29]
	s_mov_b32 m0, s50
	s_addc_u32 s1, s35, 0
	global_load_lds_dwordx4 v[0:1], off
	s_add_i32 m0, s45, 0x1c000
	v_lshl_add_u64 v[0:1], s[0:1], 0, v[184:185]
	global_load_lds_dwordx4 v[0:1], off
	v_lshl_add_u64 v[0:1], s[0:1], 0, v[204:205]
	s_add_i32 m0, s45, 0x1e000
	s_cmpk_lt_u32 s6, 0x100
	global_load_lds_dwordx4 v[0:1], off
	v_lshlrev_b32_e32 v0, 15, v9
	v_and_b32_e32 v0, 0xffff0000, v0
	v_lshl_add_u32 v0, v10, 12, v0
	v_and_b32_e32 v1, 1, v9
	v_lshl_or_b32 v0, v1, 6, v0
	v_lshl_add_u32 v206, v11, 1, v0
	v_lshlrev_b32_e32 v0, 15, v12
	v_and_b32_e32 v0, 0xffff0000, v0
	v_lshl_add_u32 v0, v13, 12, v0
	v_and_b32_e32 v1, 1, v12
	s_waitcnt vmcnt(6)
	v_lshl_or_b32 v0, v1, 6, v0
	v_lshl_add_u32 v208, v14, 1, v0
	v_mov_b32_e32 v0, 0
	s_cselect_b64 s[12:13], -1, 0
	s_ashr_i32 s51, s17, 31
	v_or_b32_e32 v234, s4, v16
	s_mov_b32 s27, 12
	v_mov_b32_e32 v207, v185
	v_mov_b32_e32 v209, v185
	s_mov_b32 s33, 0
	v_add_u32_e32 v235, 0, v17
	s_mov_b32 s52, 0
	v_mov_b32_e32 v1, v0
	v_mov_b32_e32 v2, v0
	v_mov_b32_e32 v3, v0
	v_mov_b32_e32 v4, v0
	v_mov_b32_e32 v5, v0
	v_mov_b32_e32 v6, v0
	v_mov_b32_e32 v7, v0
	v_mov_b32_e32 v8, v0
	v_mov_b32_e32 v9, v0
	v_mov_b32_e32 v10, v0
	v_mov_b32_e32 v11, v0
	v_mov_b32_e32 v12, v0
	v_mov_b32_e32 v13, v0
	v_mov_b32_e32 v14, v0
	v_mov_b32_e32 v15, v0
	v_mov_b32_e32 v16, v0
	v_mov_b32_e32 v17, v0
	v_mov_b32_e32 v18, v0
	v_mov_b32_e32 v19, v0
	v_mov_b32_e32 v20, v0
	v_mov_b32_e32 v21, v0
	v_mov_b32_e32 v22, v0
	v_mov_b32_e32 v23, v0
	v_mov_b32_e32 v24, v0
	v_mov_b32_e32 v25, v0
	v_mov_b32_e32 v26, v0
	v_mov_b32_e32 v27, v0
	v_mov_b32_e32 v28, v0
	v_mov_b32_e32 v29, v0
	v_mov_b32_e32 v30, v0
	v_mov_b32_e32 v31, v0
	v_mov_b32_e32 v32, v0
	v_mov_b32_e32 v33, v0
	v_mov_b32_e32 v34, v0
	v_mov_b32_e32 v35, v0
	v_mov_b32_e32 v36, v0
	v_mov_b32_e32 v37, v0
	v_mov_b32_e32 v38, v0
	v_mov_b32_e32 v39, v0
	v_mov_b32_e32 v40, v0
	v_mov_b32_e32 v41, v0
	v_mov_b32_e32 v42, v0
	v_mov_b32_e32 v43, v0
	v_mov_b32_e32 v44, v0
	v_mov_b32_e32 v45, v0
	v_mov_b32_e32 v46, v0
	v_mov_b32_e32 v47, v0
	v_mov_b32_e32 v48, v0
	v_mov_b32_e32 v49, v0
	v_mov_b32_e32 v50, v0
	v_mov_b32_e32 v51, v0
	v_mov_b32_e32 v52, v0
	v_mov_b32_e32 v53, v0
	v_mov_b32_e32 v54, v0
	v_mov_b32_e32 v55, v0
	v_mov_b32_e32 v56, v0
	v_mov_b32_e32 v57, v0
	v_mov_b32_e32 v58, v0
	v_mov_b32_e32 v59, v0
	v_mov_b32_e32 v60, v0
	v_mov_b32_e32 v61, v0
	v_mov_b32_e32 v62, v0
	v_mov_b32_e32 v63, v0
	v_mov_b32_e32 v64, v0
	v_mov_b32_e32 v65, v0
	v_mov_b32_e32 v66, v0
	v_mov_b32_e32 v67, v0
	v_mov_b32_e32 v68, v0
	v_mov_b32_e32 v69, v0
	v_mov_b32_e32 v70, v0
	v_mov_b32_e32 v71, v0
	v_mov_b32_e32 v72, v0
	v_mov_b32_e32 v73, v0
	v_mov_b32_e32 v74, v0
	v_mov_b32_e32 v75, v0
	v_mov_b32_e32 v76, v0
	v_mov_b32_e32 v77, v0
	v_mov_b32_e32 v78, v0
	v_mov_b32_e32 v79, v0
	v_mov_b32_e32 v80, v0
	v_mov_b32_e32 v81, v0
	v_mov_b32_e32 v82, v0
	v_mov_b32_e32 v83, v0
	v_mov_b32_e32 v84, v0
	v_mov_b32_e32 v85, v0
	v_mov_b32_e32 v86, v0
	v_mov_b32_e32 v87, v0
	v_mov_b32_e32 v88, v0
	v_mov_b32_e32 v89, v0
	v_mov_b32_e32 v90, v0
	v_mov_b32_e32 v91, v0
	v_mov_b32_e32 v92, v0
	v_mov_b32_e32 v93, v0
	v_mov_b32_e32 v94, v0
	v_mov_b32_e32 v95, v0
	v_mov_b32_e32 v96, v0
	v_mov_b32_e32 v97, v0
	v_mov_b32_e32 v98, v0
	v_mov_b32_e32 v99, v0
	v_mov_b32_e32 v100, v0
	v_mov_b32_e32 v101, v0
	v_mov_b32_e32 v102, v0
	v_mov_b32_e32 v103, v0
	v_mov_b32_e32 v104, v0
	v_mov_b32_e32 v105, v0
	v_mov_b32_e32 v106, v0
	v_mov_b32_e32 v107, v0
	v_mov_b32_e32 v108, v0
	v_mov_b32_e32 v109, v0
	v_mov_b32_e32 v110, v0
	v_mov_b32_e32 v111, v0
	v_mov_b32_e32 v112, v0
	v_mov_b32_e32 v113, v0
	v_mov_b32_e32 v114, v0
	v_mov_b32_e32 v115, v0
	v_mov_b32_e32 v116, v0
	v_mov_b32_e32 v117, v0
	v_mov_b32_e32 v118, v0
	v_mov_b32_e32 v119, v0
	v_mov_b32_e32 v120, v0
	v_mov_b32_e32 v121, v0
	v_mov_b32_e32 v122, v0
	v_mov_b32_e32 v123, v0
	v_mov_b32_e32 v124, v0
	v_mov_b32_e32 v125, v0
	v_mov_b32_e32 v126, v0
	v_mov_b32_e32 v127, v0
	s_barrier
	v_mbcnt_lo_u32_b32 v248, -1, 0
	v_mbcnt_hi_u32_b32 v248, -1, v248
	s_lshl_b32 s98, s90, 10
	s_add_i32 s98, s98, 0x22000
	v_lshl_add_u32 v246, v248, 4, s98
	v_and_b32_e32 v249, 15, v248
	v_lshrrev_b32_e32 v242, 4, v248
	v_lshrrev_b32_e32 v243, 2, v249
	v_lshl_add_u32 v242, v243, 4, v242
	v_and_b32_e32 v243, 3, v249
	v_lshl_add_u32 v242, v243, 2, v242
	v_lshl_add_u32 v247, v242, 4, s98
	v_lshrrev_b32_e32 v242, 4, v248
	v_bfe_u32 v243, v248, 2, 2
	v_lshl_add_u32 v243, v242, 2, v243
	v_sub_u32_e32 v243, v243, v249
	v_and_b32_e32 v249, 3, v248
	v_sub_u32_e32 v249, v249, v242
	v_lshlrev_b32_e32 v249, 4, v249
	s_movk_i32 s98, 0x5a00
	v_mad_i32_i24 v240, v243, s98, v249
	v_ashrrev_i32_e32 v241, 31, v240
	s_cmp_ge_u32 s90, 4
	s_cbranch_scc1 .Lprio_1174_done
	s_setprio 1

;     DI bool next(int i, Unit& u) const { const long L = (long)i * G + c; if (L >= T.nwg) return false; T.map((int)L, u.pm, u.pn); u.seg = 0; return true; }
;     DI bool next(int i, Unit& u) const { const int ti = i / 3; const long L = (long)ti * G + c; if (L >= T.nwg) return false; T.map((int)L, u.pm, u.pn); u.seg = i - 3 * ti; return true; }
;     DI const char* aptr(const Unit& u) const { return A + (size_t)u.pm * ta + (size_t)kofs(u.seg) * 2; }
;     DI const char* bptr(const Unit& u) const { return B + (size_t)u.pn * tb + (size_t)kofs(u.seg) * 2; }
; #define PG8_WAIT_V(n) asm volatile("s_waitcnt vmcnt(" #n ")" ::: "memory")
; #define PG8_BAR __builtin_amdgcn_s_barrier()
; template <class Epi, class Sched>
; DI void gemm_phase(LAS unsigned char* lds, const int wv, const int lda, const int ldb, const Sched& S, const Epi& E) {
;     ...
;     for (int i = 0; i < 2; ++i) { int R, C; stage_rc(tid * 16 + i * 8192, R, C); const int Rb = Epi::PERM ? ((R & ~31) + perm32(R & 31)) : R;
;         voffA[i] = (unsigned)(R * lda + C) * 2u; voffB[i] = (unsigned)(Rb * ldb + C) * 2u; }
;     const size_t kstep = (size_t)(BK * 2);
;     const size_t hstepA = (size_t)HALF * lda * 2, hstepB = (size_t)HALF * ldb * 2;
;     const unsigned ldsw = (unsigned)wid * 1024u;
;     const int aoff = lds_byte(wr * 64 + fr, fq * 8), boff = lds_byte(wc * 32 + fr, fq * 8);
;     ...
;     Unit cur, nxt; int ui = 0;
;     if (!S.next(0, cur)) return;
;     f32x4 acc[2][2][4][2];
; #pragma unroll
;     for (int a = 0; a < 2; ++a)
; #pragma unroll
;         for (int b = 0; b < 2; ++b)
; #pragma unroll
;             for (int m = 0; m < 4; ++m)
; #pragma unroll
;                 for (int n = 0; n < 2; ++n) acc[a][b][m][n] = (f32x4){0.f, 0.f, 0.f, 0.f};
;     bf16x8 At[4][2], B0[2][2], B1[2][2];
;     const char* cA = S.aptr(cur); const char* cB = S.bptr(cur); int nt = S.ntiles(cur);
;     PG8_STAGE(PG8_SB(0, 0), cB, voffB); PG8_STAGE(PG8_SB(0, 1), cB + hstepB, voffB); PG8_STAGE(PG8_SA(0, 0), cA, voffA); PG8_STAGE(PG8_SA(0, 1), cA + hstepA, voffA);
;     if (wr == 1) PG8_BAR;
;     PG8_WAIT_V(2); PG8_BAR;
;     PG8_STAGE(PG8_SB(1, 0), cB + kstep, voffB); PG8_STAGE(PG8_SA(1, 0), cA + kstep, voffA); PG8_STAGE(PG8_SB(1, 1), cB + hstepB + kstep, voffB);
;     PG8_WAIT_V(6); PG8_BAR;
.LBB0_1289:
	v_and_b32_e32 v15, 15, v14
	v_bfe_u32 v14, v14, 4, 2
	v_lshlrev_b32_e32 v17, 4, v14
	v_lshl_or_b32 v154, s1, 6, v15
	v_lshl_or_b32 v17, v15, 6, v17
	v_lshlrev_b32_e32 v15, 2, v15
	s_and_b32 s7, s0, 3
	s_lshl_b32 s0, s1, 13
	v_and_b32_e32 v18, 32, v15
	s_add_i32 m0, s27, 0x18000
	v_lshl_add_u64 v[6:7], v[6:7], 0, s[28:29]
	v_bitop3_b32 v19, v17, s0, v18 bitop3:0xde
	s_lshl_b32 s0, s7, 12
	s_waitcnt vmcnt(2)
	s_barrier
	global_load_lds_dwordx4 v[6:7], off
	v_lshl_add_u64 v[4:5], v[4:5], 0, s[28:29]
	s_add_i32 m0, s27, 0x1a000
	s_add_i32 s45, s27, 0x8000
	s_add_i32 s46, s27, 0xa000
	v_bitop3_b32 v155, v17, s0, v18 bitop3:0xde
	global_load_lds_dwordx4 v[4:5], off
	v_lshl_add_u64 v[0:1], v[0:1], 0, s[28:29]
	s_mov_b32 m0, s45
	s_add_u32 s0, s34, 0x80080
	global_load_lds_dwordx4 v[0:1], off
	v_lshl_add_u64 v[0:1], v[2:3], 0, s[28:29]
	s_mov_b32 m0, s46
	s_addc_u32 s1, s35, 0
	global_load_lds_dwordx4 v[0:1], off
	s_add_i32 m0, s27, 0x1c000
	v_lshl_add_u64 v[0:1], s[0:1], 0, v[184:185]
	global_load_lds_dwordx4 v[0:1], off
	v_lshl_add_u64 v[0:1], s[0:1], 0, v[136:137]
	s_add_i32 m0, s27, 0x1e000
	s_movk_i32 s0, 0x80
	global_load_lds_dwordx4 v[0:1], off
	v_lshlrev_b32_e32 v0, 6, v14
	v_bitop3_b32 v157, v0, 64, v15 bitop3:0x36
	v_bitop3_b32 v158, v0, s0, v15 bitop3:0x36
	v_lshlrev_b32_e32 v0, 15, v8
	v_and_b32_e32 v0, 0xffff0000, v0
	v_lshl_add_u32 v0, v9, 12, v0
	v_and_b32_e32 v1, 1, v8
	s_cmpk_lt_u32 s6, 0x100
	v_lshl_or_b32 v0, v1, 6, v0
	s_cselect_b64 s[12:13], -1, 0
	s_ashr_i32 s48, s20, 31
	s_ashr_i32 s49, s17, 31
	s_lshl_b32 s0, s7, 2
	v_lshl_add_u32 v138, v10, 1, v0
	v_lshlrev_b32_e32 v0, 15, v11
	s_add_u32 s0, s10, s0
	v_and_b32_e32 v0, 0xffff0000, v0
	s_waitcnt vmcnt(6)
	s_addc_u32 s1, s11, 0
	v_lshl_add_u32 v0, v12, 12, v0
	v_and_b32_e32 v1, 1, v11
	v_lshlrev_b32_e32 v16, 3, v14
	s_add_u32 s50, s0, 0x49c28000
	v_lshl_or_b32 v0, v1, 6, v0
	v_lshl_or_b32 v156, s7, 5, v16
	s_mov_b32 s47, 0
	v_cmp_eq_u32_e64 s[4:5], 0, v14
	s_addc_u32 s51, s1, 0
	v_mov_b32_e32 v139, v185
	v_lshl_add_u32 v140, v13, 1, v0
	v_mov_b32_e32 v141, v185
	v_add_u32_e32 v159, 0, v19
	s_barrier
	v_mbcnt_lo_u32_b32 v248, -1, 0
	v_mbcnt_hi_u32_b32 v248, -1, v248
	s_lshl_b32 s98, s90, 10
	s_add_i32 s98, s98, 0x22000
	v_lshl_add_u32 v246, v248, 4, s98
	v_and_b32_e32 v249, 15, v248
	v_lshrrev_b32_e32 v242, 4, v248
	v_lshrrev_b32_e32 v243, 2, v249
	v_lshl_add_u32 v242, v243, 4, v242
	v_and_b32_e32 v243, 3, v249
	v_lshl_add_u32 v242, v243, 2, v242
	v_lshl_add_u32 v247, v242, 4, s98
	v_lshrrev_b32_e32 v242, 4, v248
	v_bfe_u32 v243, v248, 2, 2
	v_lshl_add_u32 v243, v242, 2, v243
	v_sub_u32_e32 v243, v243, v249
	v_and_b32_e32 v249, 3, v248
	v_sub_u32_e32 v249, v249, v242
	v_lshlrev_b32_e32 v249, 4, v249
	s_movk_i32 s98, 0x1000
	v_mad_i32_i24 v240, v243, s98, v249
	v_ashrrev_i32_e32 v241, 31, v240
	s_cmp_ge_u32 s90, 4
	s_cbranch_scc1 .Lprio_1292_done
	s_setprio 1

;     DI bool next(int i, Unit& u) const { const long L = (long)i * G + c; if (L >= T.nwg) return false; T.map((int)L, u.pm, u.pn); u.seg = 0; return true; }
;     DI bool next(int i, Unit& u) const { const int ti = i / 3; const long L = (long)ti * G + c; if (L >= T.nwg) return false; T.map((int)L, u.pm, u.pn); u.seg = i - 3 * ti; return true; }
;     DI const char* aptr(const Unit& u) const { return A + (size_t)u.pm * ta + (size_t)kofs(u.seg) * 2; }
;     DI const char* bptr(const Unit& u) const { return B + (size_t)u.pn * tb + (size_t)kofs(u.seg) * 2; }
; #define PG8_WAIT_V(n) asm volatile("s_waitcnt vmcnt(" #n ")" ::: "memory")
; #define PG8_BAR __builtin_amdgcn_s_barrier()
; template <class Epi, class Sched>
; DI void gemm_phase(LAS unsigned char* lds, const int wv, const int lda, const int ldb, const Sched& S, const Epi& E) {
;     ...
;     for (int i = 0; i < 2; ++i) { int R, C; stage_rc(tid * 16 + i * 8192, R, C); const int Rb = Epi::PERM ? ((R & ~31) + perm32(R & 31)) : R;
;         voffA[i] = (unsigned)(R * lda + C) * 2u; voffB[i] = (unsigned)(Rb * ldb + C) * 2u; }
;     const size_t kstep = (size_t)(BK * 2);
;     const size_t hstepA = (size_t)HALF * lda * 2, hstepB = (size_t)HALF * ldb * 2;
;     const unsigned ldsw = (unsigned)wid * 1024u;
;     const int aoff = lds_byte(wr * 64 + fr, fq * 8), boff = lds_byte(wc * 32 + fr, fq * 8);
;     ...
;     Unit cur, nxt; int ui = 0;
;     if (!S.next(0, cur)) return;
;     f32x4 acc[2][2][4][2];
; #pragma unroll
;     for (int a = 0; a < 2; ++a)
; #pragma unroll
;         for (int b = 0; b < 2; ++b)
; #pragma unroll
;             for (int m = 0; m < 4; ++m)
; #pragma unroll
;                 for (int n = 0; n < 2; ++n) acc[a][b][m][n] = (f32x4){0.f, 0.f, 0.f, 0.f};
;     bf16x8 At[4][2], B0[2][2], B1[2][2];
;     const char* cA = S.aptr(cur); const char* cB = S.bptr(cur); int nt = S.ntiles(cur);
;     PG8_STAGE(PG8_SB(0, 0), cB, voffB); PG8_STAGE(PG8_SB(0, 1), cB + hstepB, voffB); PG8_STAGE(PG8_SA(0, 0), cA, voffA); PG8_STAGE(PG8_SA(0, 1), cA + hstepA, voffA);
;     if (wr == 1) PG8_BAR;
;     PG8_WAIT_V(2); PG8_BAR;
;     PG8_STAGE(PG8_SB(1, 0), cB + kstep, voffB); PG8_STAGE(PG8_SA(1, 0), cA + kstep, voffA); PG8_STAGE(PG8_SB(1, 1), cB + hstepB + kstep, voffB);
;     PG8_WAIT_V(6); PG8_BAR;
.LBB0_1387:
	s_sext_i32_i16 s47, s4
	s_lshl_b32 s4, s17, 13
	s_and_b32 s4, s4, 0xe000
	s_sub_i32 s42, 0, s4
	v_lshrrev_b32_e32 v16, 1, v14
	s_add_i32 s42, s42, 0x20000
	v_and_b32_e32 v16, 24, v16
	s_add_u32 s6, s10, 0x23c28000
	v_and_b32_e32 v15, 15, v14
	v_lshlrev_b32_e32 v17, 1, v16
	v_lshlrev_b32_e32 v14, 2, v14
	s_addc_u32 s7, s11, 0
	v_lshl_or_b32 v144, s0, 6, v15
	v_lshl_or_b32 v15, v15, 6, v17
	s_lshl_b32 s0, s0, 13
	v_and_b32_e32 v14, 32, v14
	v_bitop3_b32 v17, v15, s0, v14 bitop3:0xde
	s_lshl_b32 s0, s1, 5
	s_and_b32 s4, s0, 0x60
	s_add_i32 m0, s25, 0x18000
	v_lshl_add_u64 v[6:7], v[6:7], 0, s[28:29]
	s_lshl_b32 s0, s4, 7
	s_waitcnt vmcnt(2)
	s_barrier
	global_load_lds_dwordx4 v[6:7], off
	v_lshl_add_u64 v[4:5], v[4:5], 0, s[28:29]
	s_add_i32 m0, s25, 0x1a000
	s_add_i32 s43, s25, 0x8000
	s_add_i32 s44, s25, 0xa000
	v_bitop3_b32 v145, v15, s0, v14 bitop3:0xde
	global_load_lds_dwordx4 v[4:5], off
	v_lshl_add_u64 v[0:1], v[0:1], 0, s[28:29]
	s_mov_b32 m0, s43
	s_add_u32 s0, s30, 0x80080
	global_load_lds_dwordx4 v[0:1], off
	v_lshl_add_u64 v[0:1], v[2:3], 0, s[28:29]
	s_mov_b32 m0, s44
	s_addc_u32 s1, s31, 0
	global_load_lds_dwordx4 v[0:1], off
	s_add_i32 m0, s25, 0x1c000
	v_lshl_add_u64 v[0:1], s[0:1], 0, v[184:185]
	global_load_lds_dwordx4 v[0:1], off
	v_lshl_add_u64 v[0:1], s[0:1], 0, v[132:133]
	s_add_i32 m0, s25, 0x1e000
	s_cmpk_lt_u32 s5, 0x100
	global_load_lds_dwordx4 v[0:1], off
	v_lshlrev_b32_e32 v0, 15, v8
	v_and_b32_e32 v0, 0xffff0000, v0
	v_lshl_add_u32 v0, v9, 12, v0
	v_and_b32_e32 v1, 1, v8
	v_lshl_or_b32 v0, v1, 6, v0
	v_lshl_add_u32 v134, v10, 1, v0
	v_lshlrev_b32_e32 v0, 15, v11
	v_and_b32_e32 v0, 0xffff0000, v0
	s_waitcnt vmcnt(6)
	v_lshl_add_u32 v0, v12, 12, v0
	v_and_b32_e32 v1, 1, v11
	v_lshl_or_b32 v0, v1, 6, v0
	s_cselect_b64 s[10:11], -1, 0
	s_ashr_i32 s45, s20, 31
	v_or_b32_e32 v146, s4, v16
	v_mov_b32_e32 v135, v185
	v_lshl_add_u32 v136, v13, 1, v0
	v_mov_b32_e32 v137, v185
	s_mov_b32 s46, 0
	v_add_u32_e32 v147, 0, v17
	s_barrier
	s_cmp_ge_u32 s90, 4
	s_cbranch_scc1 .Lprio_1390_done
	s_setprio 1

;     DI bool next(int i, Unit& u) const { const long L = (long)i * G + c; if (L >= T.nwg) return false; T.map((int)L, u.pm, u.pn); u.seg = 0; return true; }
;     DI bool next(int i, Unit& u) const { const int ti = i / 3; const long L = (long)ti * G + c; if (L >= T.nwg) return false; T.map((int)L, u.pm, u.pn); u.seg = i - 3 * ti; return true; }
;     DI const char* aptr(const Unit& u) const { return A + (size_t)u.pm * ta + (size_t)kofs(u.seg) * 2; }
;     DI const char* bptr(const Unit& u) const { return B + (size_t)u.pn * tb + (size_t)kofs(u.seg) * 2; }
; #define PG8_WAIT_V(n) asm volatile("s_waitcnt vmcnt(" #n ")" ::: "memory")
; #define PG8_BAR __builtin_amdgcn_s_barrier()
; template <class Epi, class Sched>
; DI void gemm_phase(LAS unsigned char* lds, const int wv, const int lda, const int ldb, const Sched& S, const Epi& E) {
;     ...
;     for (int i = 0; i < 2; ++i) { int R, C; stage_rc(tid * 16 + i * 8192, R, C); const int Rb = Epi::PERM ? ((R & ~31) + perm32(R & 31)) : R;
;         voffA[i] = (unsigned)(R * lda + C) * 2u; voffB[i] = (unsigned)(Rb * ldb + C) * 2u; }
;     const size_t kstep = (size_t)(BK * 2);
;     const size_t hstepA = (size_t)HALF * lda * 2, hstepB = (size_t)HALF * ldb * 2;
;     const unsigned ldsw = (unsigned)wid * 1024u;
;     const int aoff = lds_byte(wr * 64 + fr, fq * 8), boff = lds_byte(wc * 32 + fr, fq * 8);
;     ...
;     Unit cur, nxt; int ui = 0;
;     if (!S.next(0, cur)) return;
;     f32x4 acc[2][2][4][2];
; #pragma unroll
;     for (int a = 0; a < 2; ++a)
; #pragma unroll
;         for (int b = 0; b < 2; ++b)
; #pragma unroll
;             for (int m = 0; m < 4; ++m)
; #pragma unroll
;                 for (int n = 0; n < 2; ++n) acc[a][b][m][n] = (f32x4){0.f, 0.f, 0.f, 0.f};
;     bf16x8 At[4][2], B0[2][2], B1[2][2];
;     const char* cA = S.aptr(cur); const char* cB = S.bptr(cur); int nt = S.ntiles(cur);
;     PG8_STAGE(PG8_SB(0, 0), cB, voffB); PG8_STAGE(PG8_SB(0, 1), cB + hstepB, voffB); PG8_STAGE(PG8_SA(0, 0), cA, voffA); PG8_STAGE(PG8_SA(0, 1), cA + hstepA, voffA);
;     if (wr == 1) PG8_BAR;
;     PG8_WAIT_V(2); PG8_BAR;
;     PG8_STAGE(PG8_SB(1, 0), cB + kstep, voffB); PG8_STAGE(PG8_SA(1, 0), cA + kstep, voffA); PG8_STAGE(PG8_SB(1, 1), cB + hstepB + kstep, voffB);
;     PG8_WAIT_V(6); PG8_BAR;
.LBB0_1467:
	s_add_u32 s4, s10, 0x1fc28000
	v_and_b32_e32 v15, 15, v14
	v_bfe_u32 v14, v14, 4, 2
	s_addc_u32 s5, s11, 0
	v_lshlrev_b32_e32 v17, 4, v14
	s_cmp_eq_u32 s71, 3
	v_lshl_or_b32 v154, s1, 6, v15
	v_lshl_or_b32 v17, v15, 6, v17
	v_lshlrev_b32_e32 v15, 2, v15
	s_cselect_b32 s13, s5, s9
	s_cselect_b32 s12, s4, s8
	s_and_b32 s7, s0, 3
	s_lshl_b32 s0, s1, 13
	v_and_b32_e32 v18, 32, v15
	s_add_i32 m0, s31, 0x18000
	v_lshl_add_u64 v[6:7], v[6:7], 0, s[28:29]
	v_bitop3_b32 v19, v17, s0, v18 bitop3:0xde
	s_lshl_b32 s0, s7, 12
	s_waitcnt vmcnt(2)
	s_barrier
	global_load_lds_dwordx4 v[6:7], off
	v_lshl_add_u64 v[4:5], v[4:5], 0, s[28:29]
	s_add_i32 m0, s31, 0x1a000
	s_add_i32 s47, s31, 0x8000
	s_add_i32 s48, s31, 0xa000
	v_bitop3_b32 v155, v17, s0, v18 bitop3:0xde
	global_load_lds_dwordx4 v[4:5], off
	v_lshl_add_u64 v[0:1], v[0:1], 0, s[28:29]
	s_mov_b32 m0, s47
	s_add_u32 s0, s36, 0x200080
	global_load_lds_dwordx4 v[0:1], off
	v_lshl_add_u64 v[0:1], v[2:3], 0, s[28:29]
	s_mov_b32 m0, s48
	s_addc_u32 s1, s37, 0
	global_load_lds_dwordx4 v[0:1], off
	s_add_i32 m0, s31, 0x1c000
	v_lshl_add_u64 v[0:1], s[0:1], 0, v[184:185]
	global_load_lds_dwordx4 v[0:1], off
	v_lshl_add_u64 v[0:1], s[0:1], 0, v[136:137]
	s_add_i32 m0, s31, 0x1e000
	s_movk_i32 s0, 0x80
	global_load_lds_dwordx4 v[0:1], off
	v_lshlrev_b32_e32 v0, 6, v14
	v_bitop3_b32 v157, v0, 64, v15 bitop3:0x36
	v_bitop3_b32 v158, v0, s0, v15 bitop3:0x36
	v_lshlrev_b32_e32 v0, 17, v8
	v_and_b32_e32 v0, 0xfffc0000, v0
	v_lshl_add_u32 v0, v9, 14, v0
	v_and_b32_e32 v1, 1, v8
	s_cmpk_lt_u32 s6, 0x100
	v_lshl_or_b32 v0, v1, 6, v0
	s_cselect_b64 s[14:15], -1, 0
	s_ashr_i32 s50, s20, 31
	s_ashr_i32 s51, s17, 31
	s_lshl_b32 s0, s7, 2
	v_lshl_add_u32 v138, v10, 1, v0
	v_lshlrev_b32_e32 v0, 17, v11
	s_add_u32 s0, s10, s0
	v_and_b32_e32 v0, 0xfffc0000, v0
	s_waitcnt vmcnt(6)
	s_addc_u32 s1, s11, 0
	v_lshl_add_u32 v0, v12, 14, v0
	v_and_b32_e32 v1, 1, v11
	v_lshlrev_b32_e32 v16, 3, v14
	s_add_u32 s52, s0, 0x49c28000
	v_lshl_or_b32 v0, v1, 6, v0
	v_lshl_or_b32 v156, s7, 5, v16
	s_mov_b32 s49, 0
	v_cmp_eq_u32_e64 s[4:5], 0, v14
	s_addc_u32 s53, s1, 0
	v_mov_b32_e32 v139, v185
	v_lshl_add_u32 v140, v13, 1, v0
	v_mov_b32_e32 v141, v185
	v_add_u32_e32 v159, 0, v19
	s_barrier
	v_mbcnt_lo_u32_b32 v248, -1, 0
	v_mbcnt_hi_u32_b32 v248, -1, v248
	s_lshl_b32 s98, s90, 10
	s_add_i32 s98, s98, 0x22000
	v_lshl_add_u32 v246, v248, 4, s98
	v_and_b32_e32 v249, 15, v248
	v_lshrrev_b32_e32 v242, 4, v248
	v_lshrrev_b32_e32 v243, 2, v249
	v_lshl_add_u32 v242, v243, 4, v242
	v_and_b32_e32 v243, 3, v249
	v_lshl_add_u32 v242, v243, 2, v242
	v_lshl_add_u32 v247, v242, 4, s98
	v_lshrrev_b32_e32 v242, 4, v248
	v_bfe_u32 v243, v248, 2, 2
	v_lshl_add_u32 v243, v242, 2, v243
	v_sub_u32_e32 v243, v243, v249
	v_and_b32_e32 v249, 3, v248
	v_sub_u32_e32 v249, v249, v242
	v_lshlrev_b32_e32 v249, 4, v249
	s_movk_i32 s98, 0x1000
	v_mad_i32_i24 v240, v243, s98, v249
	v_ashrrev_i32_e32 v241, 31, v240
	s_cmp_ge_u32 s90, 4
	s_cbranch_scc1 .Lprio_1470_done
	s_setprio 1
